# v57 + NA unit prologue: bias-table load kept in flight across the first K/V LDS-DMA and Q load issues (consumed before the prologue's first barrier)
# baseline (speedup 1.0000x reference)
; __device__ __forceinline__ int opaque_tid() { int t; asm volatile("v_mov_b32 %0, %1" : "=v"(t) : "v"((int)threadIdx.x)); return t; }
; #define WAIT_BAR(N) asm volatile("s_waitcnt vmcnt(" #N ") lgkmcnt(0)\n\ts_barrier" ::: "memory")
; #define DMA_K(t, slot) glds16s(kvo, Kh + (long)TROW(t) * PITCH, (unsigned)__builtin_amdgcn_readfirstlane(kdst + (slot)))
; #define DMA_V(t, slot) glds16s(vvo, Vh + (long)TROW(t) * PITCH, (unsigned)__builtin_amdgcn_readfirstlane(vdst + (slot)))
;     ...
;     const char* Kbase = shm + LDS_K; bf16x8 kf[8];
;     const lds_cptr shm3 = (lds_cptr)shm; const lds_cptr kp0 = shm3 + LDS_K + hi * 1024 + r32 * 16; const lds_cptr vp0 = shm3 + LDS_V + ((lane >> 4) & 1) * 32 + (lane & 3) * 8 + (4 * hi + ((lane & 15) >> 2)) * 64;
;     DMA_K(0, 0); DMA_V(0, 0); DMA_K(1, SLOTB);
;     bf16x8 qr[4];
; #pragma unroll
;     for (int d0 = 0; d0 < 4; ++d0) qr[d0] = *reinterpret_cast<const bf16x8*>(&Qw[(long)r32 * PITCH + d0 * 16 + hi * 8]);
;     float mhat = (MODE == 0) ? bref : 0.f, l_reg = 0.f; f32x16 o[2]; o[0] = f32x16{}; o[1] = f32x16{}; f32x16 negm = f32x16{};
;     if (MODE == 0) { _Pragma("unroll") for (int r = 0; r < 16; ++r) negm[r] = -bref; }
;     if (MODE != 1) asm volatile("" : "+v"(negm));
;     int na_gr = 0, na_rs = 0, na_qc = 0, na_cs = 0;
;     if (MODE == 1) { na_gr = r0 + (wid >> 1); na_rs = min(max(na_gr - 4, 0), 120); na_qc = 32 * (wid & 1) + r32; na_cs = min(max(na_qc - 8, 0), 48); }
;     ...
;     bool resc = false;
;     ...
;     f32x16 pA0, pA1, pB0, pB1;
;     int sl_prev = 0, sl_cur = 0, sl_next = SLOTB;
;     ...
;     DMA_K(2, 2 * SLOTB);
;     WAIT_BAR(3);
;     qkt(pA0, pA1, Kbase, qr, negm, r32, hi); asm volatile("s_nop 15\n\ts_nop 7" : "+v"(pA0), "+v"(pA1));
;     START(pA0, pA1);
;     _Pragma("unroll") for (int r = 0; r < 16; ++r) pA1[r] = __builtin_amdgcn_exp2f(pA1[r]);
;     WAIT_BAR(0);
; __global__ void __launch_bounds__(NTHREADS, 2) mega_fwd(Params P) {
;     ...
;                     { float* bl = (float*)((char*)lds + ap::LDS_NABIAS); const float* src = P.rpb + ((size_t)l * 6 + h) * 465; for (int i = opaque_tid(); i < 465; i += NTHREADS) bl[i] = src[i] * LOG2E; }
;                     __syncthreads();
.LBB0_588:
	global_load_dword v242, v[4:5], off
	v_add_u32_e32 v0, 0x200, v0
	s_movk_i32 s6, 0xffd0
	v_cmp_lt_i32_e32 vcc, s6, v0
	v_lshl_add_u64 v[4:5], v[4:5], 0, s[24:25]
	s_or_b64 s[4:5], vcc, s[4:5]
	v_mov_b32_e32 v243, v2
	v_add_u32_e32 v2, 0x800, v2
	s_andn2_b64 exec, exec, s[4:5]
	s_cbranch_execnz .LBB0_588
.LBB0_589:
	s_or_b64 exec, exec, s[0:1]
	s_and_b32 s3, 0xffff, s3
	s_lshl_b32 s0, s3, 2
	v_sub_u32_e64 v2, s0, 1 clamp
	v_sub_u32_e64 v0, s0, 4 clamp
	v_readfirstlane_b32 s1, v2
	s_min_u32 s1, s1, 0x78
	v_readfirstlane_b32 s89, v0
	s_sub_i32 s1, s1, s89
	s_add_i32 s19, s1, 7
	s_and_b32 s21, s19, -2
	s_lshl_b32 s1, s3, 8
	s_cmp_gt_u32 s2, 5
	v_writelane_b32 v252, s3, 27
	s_cselect_b64 s[2:3], -1, 0
	v_writelane_b32 v252, s2, 28
	s_waitcnt lgkmcnt(0)
	s_barrier
	v_readfirstlane_b32 s100, v214
	s_nop 0
	s_lshr_b32 s100, s100, 6
	s_cmp_ge_u32 s100, 4
	s_cbranch_scc0 .Lna_prio_skip
	s_setprio 1
.Lna_prio_skip:
	v_writelane_b32 v252, s3, 29
	s_and_b64 s[2:3], s[2:3], exec
	s_cselect_b32 s4, 0x2100, 0
	s_cselect_b32 s5, 0x2520000, 0
	s_add_i32 s86, s4, s1
	s_mov_b64 s[2:3], s[76:77]
	s_mul_hi_u32 s4, s86, 0x1200
	v_writelane_b32 v252, s86, 30
	s_mul_i32 s6, s86, 0x1200
	s_add_u32 s6, s2, s6
	s_addc_u32 s4, s3, s4
	s_lshl_b32 s8, s28, 7
	s_mov_b64 s[2:3], s[76:77]
	s_add_u32 s10, s6, s8
	s_addc_u32 s4, s4, 0
	s_add_u32 s2, s2, s5
	s_addc_u32 s3, s3, 0
	s_add_u32 s6, s2, s8
	s_addc_u32 s7, s3, 0
	s_add_u32 s93, s6, 0xe400b00
	s_mov_b64 s[2:3], s[76:77]
	s_addc_u32 s94, s7, 0
	s_add_u32 s2, s2, s5
	s_addc_u32 s3, s3, 0
	s_add_u32 s8, s2, s8
	s_addc_u32 s9, s3, 0
	s_mov_b64 s[2:3], s[76:77]
	v_writelane_b32 v252, s87, 31
	s_add_u32 s91, s8, 0xe400e00
	v_writelane_b32 v252, s2, 32
	s_addc_u32 s92, s9, 0
	s_mov_b32 s95, 1
	v_writelane_b32 v252, s3, 33
	s_mov_b64 s[2:3], s[76:77]
	v_mov_b32 v223, v214
	s_mov_b32 s72, 0
	v_readfirstlane_b32 s5, v223
	v_writelane_b32 v252, s2, 34
	s_ashr_i32 s12, s5, 6
	s_lshl_b32 s16, s12, 5
	v_writelane_b32 v252, s3, 35
	s_mul_i32 s2, s12, 0x24000
	s_mul_hi_i32 s3, s16, 0x1200
	s_add_u32 s10, s10, s2
	s_addc_u32 s11, s4, s3
	s_lshl_b32 s2, s12, 4
	v_and_b32_e32 v224, 63, v223
	v_mov_b32_e32 v0, s2
	v_mad_u32_u24 v234, v224, s80, v0
	v_bfe_u32 v0, v223, 2, 4
	v_and_or_b32 v0, s2, 48, v0
	s_ashr_i32 s2, s5, 3
	s_and_b32 s3, s5, 0x3fffffc0
	s_and_b32 s2, s2, 0x7fffffe0
	s_lshl_b32 s4, s12, 10
	v_mov_b32_e32 v2, s2
	s_cmp_lg_u32 0, -1
	v_mad_u32_u24 v0, v0, s81, v2
	v_lshlrev_b32_e32 v2, 3, v223
	s_cselect_b32 s2, 0, 0
	v_and_b32_e32 v227, 24, v2
	s_add_i32 s4, s4, s2
	v_and_b32_e32 v225, 31, v223
	v_or_b32_e32 v0, v0, v227
	s_add_i32 s90, s4, 0x6000
	v_lshlrev_b32_e32 v235, 1, v0
	v_writelane_b32 v252, s12, 36
	s_add_u32 s12, s6, 0x10800b00
	v_mul_u32_u24_e32 v0, 0x900, v225
	v_bfe_u32 v230, v223, 5, 1
	s_addc_u32 s13, s7, 0
	v_lshlrev_b32_e32 v0, 1, v0
	s_mov_b32 s2, m0
	s_mov_b32 m0, s4
	s_nop 0
	global_load_lds_dwordx4 v234, s[12:13]
	s_mov_b32 m0, s2
	s_add_u32 s12, s8, 0x10800e00
	v_lshl_or_b32 v0, v230, 4, v0
	s_addc_u32 s13, s9, 0
	v_lshl_add_u64 v[2:3], s[10:11], 0, v[0:1]
	s_mov_b32 s2, m0
	s_mov_b32 m0, s90
	s_nop 0
	global_load_lds_dwordx4 v235, s[12:13]
	s_mov_b32 m0, s2
	s_add_u32 s12, s6, 0x10848b00
	v_add_co_u32_e32 v4, vcc, s82, v2
	s_addc_u32 s13, s7, 0
	s_add_i32 s2, s4, 0x2000
	s_mov_b32 s14, m0
	s_mov_b32 m0, s2
	s_nop 0
	global_load_lds_dwordx4 v234, s[12:13]
	s_mov_b32 m0, s14
	v_addc_co_u32_e32 v5, vcc, 0, v3, vcc
	flat_load_dwordx4 v[144:147], v[4:5] offset:2048
	s_mov_b64 s[10:11], 0xe400800
	v_lshl_add_u64 v[2:3], v[2:3], 0, s[10:11]
	flat_load_dwordx4 v[140:143], v[2:3] offset:32
	flat_load_dwordx4 v[136:139], v[2:3] offset:64
	flat_load_dwordx4 v[132:135], v[2:3] offset:96
	s_ashr_i32 vcc_lo, s5, 7
	s_add_i32 s2, vcc_lo, s0
	s_max_i32 s10, s2, 4
	s_add_i32 s10, s10, -4
	s_add_u32 s12, s6, 0x10890b00
	v_lshlrev_b32_e32 v0, 10, v230
	v_lshlrev_b32_e32 v2, 4, v225
	v_writelane_b32 v252, s2, 37
	s_addc_u32 s13, s7, 0
	s_add_i32 s2, s4, 0x4000
	s_mov_b32 s11, m0
	s_mov_b32 m0, s2
	s_nop 0
	global_load_lds_dwordx4 v234, s[12:13]
	s_mov_b32 m0, s11
	v_add3_u32 v236, 0, v0, v2
	s_movk_i32 s100, 0x1d1
	v_cmp_gt_u32_e64 s[100:101], s100, v214
	s_mov_b64 exec, s[100:101]
	s_waitcnt vmcnt(8)
	v_mul_f32_e32 v242, 0x3fb8aa3b, v242
	ds_write_b32 v243, v242
	s_mov_b64 exec, -1
	s_mov_b32 s101, 0
	s_waitcnt vmcnt(3) lgkmcnt(0)
	s_barrier
	ds_read_b128 v[2:5], v236
	ds_read_b128 v[6:9], v236 offset:512
	s_lshl_b32 s3, s3, 2
	s_add_i32 s3, s3, 0
	s_min_u32 s20, s10, 0x78
	s_add_u32 s6, s6, 0x108d8b00
	s_waitcnt vmcnt(0) lgkmcnt(0)
	v_mfma_f32_32x32x16_bf16 v[34:49], v[2:5], v[144:147], 0
	s_addc_u32 s7, s7, 0
	s_mov_b32 s12, s16
	v_writelane_b32 v252, s12, 38
	v_lshlrev_b32_e32 v0, 1, v223
	v_and_b32_e32 v228, 32, v0
	v_writelane_b32 v252, s13, 39
	v_writelane_b32 v252, s19, 40
	v_mfma_f32_32x32x16_bf16 v[18:33], v[6:9], v[144:147], 0
	ds_read_b128 v[2:5], v236 offset:2048
	ds_read_b128 v[6:9], v236 offset:2560
	v_lshlrev_b32_e32 v226, 8, v230
	v_and_or_b32 v233, s16, 32, v225
	v_add_u32_e32 v0, 0, v228
	v_lshlrev_b32_e32 v196, 2, v225
	s_movk_i32 s88, 0x2000
	s_movk_i32 s2, 0x4000
	s_waitcnt lgkmcnt(1)
	v_mfma_f32_32x32x16_bf16 v[34:49], v[2:5], v[140:143], v[34:49]
	ds_read_b128 v[2:5], v236 offset:4608
	ds_read_b128 v[10:13], v236 offset:4096
	v_add_u32_e32 v238, s3, v196
	s_waitcnt lgkmcnt(2)
	v_mfma_f32_32x32x16_bf16 v[18:33], v[6:9], v[140:143], v[18:33]
	s_waitcnt lgkmcnt(0)
	v_mfma_f32_32x32x16_bf16 v[34:49], v[10:13], v[136:139], v[34:49]
	ds_read_b128 v[6:9], v236 offset:6656
	ds_read_b128 v[10:13], v236 offset:6144
	v_mfma_f32_32x32x16_bf16 v[18:33], v[2:5], v[136:139], v[18:33]
	v_lshlrev_b32_e32 v2, 4, v223
	v_and_or_b32 v229, v2, s83, v226
	v_sub_u32_e64 v2, v233, 8 clamp
	v_add3_u32 v237, v0, v227, v229
	v_min_u32_e32 v232, 48, v2
	s_waitcnt lgkmcnt(0)
	v_mfma_f32_32x32x16_bf16 v[34:49], v[10:13], v[132:135], v[34:49]
	v_mfma_f32_32x32x16_bf16 v[18:33], v[6:9], v[132:135], v[18:33]
	s_nop 15
	s_nop 7
	s_waitcnt vmcnt(0) lgkmcnt(0)
	s_barrier
; __device__ __forceinline__ float max3f(float a, float b, float c) { float r; asm("v_max3_f32 %0, %1, %2, %3" : "=v"(r) : "v"(a), "v"(b), "v"(c)); return r; }
; __device__ __forceinline__ float max2f(float a, float b) { float r; asm("v_max_f32_e32 %0, %1, %2" : "=v"(r) : "v"(a), "v"(b)); return r; }
; #define WAIT_BAR(N) asm volatile("s_waitcnt vmcnt(" #N ") lgkmcnt(0)\n\ts_barrier" ::: "memory")
; #define DMA_K(t, slot) glds16s(kvo, Kh + (long)TROW(t) * PITCH, (unsigned)__builtin_amdgcn_readfirstlane(kdst + (slot)))
; #define DMA_V(t, slot) glds16s(vvo, Vh + (long)TROW(t) * PITCH, (unsigned)__builtin_amdgcn_readfirstlane(vdst + (slot)))
; #define ROT() do { sl_prev = sl_cur; sl_cur = sl_next; sl_next = (sl_next == (NSLOT - 1) * SLOTB) ? 0 : sl_next + SLOTB; } while (0)
; __device__ __forceinline__ float rowmax(const f32x16& p0, const f32x16& p1) {
;     float a = max3f(p0[0], p0[1], p1[0]), b = max3f(p0[2], p0[3], p1[1]); a = max3f(a, p1[2], p1[3]);
; #pragma unroll
;     for (int r = 4; r < 16; r += 4) { a = max3f(a, p0[r], p0[r + 1]); b = max3f(b, p0[r + 2], p0[r + 3]); a = max3f(a, p1[r], p1[r + 1]); b = max3f(b, p1[r + 2], p1[r + 3]); }
;     const float m = max2f(a, b);
;     auto rr = __builtin_amdgcn_permlane32_swap(__float_as_uint(m), __float_as_uint(m), false, false);
;     return max2f(__uint_as_float(rr[0]), __uint_as_float(rr[1]));
; }
;     ...
;     f32x16 pA0, pA1, pB0, pB1;
;     int sl_prev = 0, sl_cur = 0, sl_next = SLOTB;
;     ...
;     DMA_K(2, 2 * SLOTB);
;     WAIT_BAR(3);
;     qkt(pA0, pA1, Kbase, qr, negm, r32, hi); asm volatile("s_nop 15\n\ts_nop 7" : "+v"(pA0), "+v"(pA1));
;     START(pA0, pA1);
;     _Pragma("unroll") for (int r = 0; r < 16; ++r) pA1[r] = __builtin_amdgcn_exp2f(pA1[r]);
;     WAIT_BAR(0);
;     DMA_K(3, 0); DMA_V(1, SLOTB);
;     ROT();
;     kload8(kf, kp0 + sl_cur);
;     WAIT_BAR(2);
	s_mov_b32 s10, m0
	s_mov_b32 m0, s4
	s_nop 0
	global_load_lds_dwordx4 v234, s[6:7]
	s_mov_b32 m0, s10
	s_add_u32 s6, s8, 0x10848e00
	v_max3_f32 v3, v34, v35, v18
	v_max3_f32 v4, v36, v37, v19
	s_addc_u32 s7, s9, 0
	v_max3_f32 v3, v3, v20, v21
	v_max3_f32 v4, v4, v40, v41
	s_add_i32 s8, s4, 0x8000
	v_max3_f32 v3, v3, v38, v39
	v_max3_f32 v4, v4, v24, v25
	s_mov_b32 s9, m0
	s_mov_b32 m0, s8
	s_nop 0
	global_load_lds_dwordx4 v235, s[6:7]
	s_mov_b32 m0, s9
	ds_read_b128 v[176:179], v236 offset:8192
	ds_read_b128 v[168:171], v236 offset:8704
	ds_read_b128 v[172:175], v236 offset:10240
	ds_read_b128 v[164:167], v236 offset:10752
	ds_read_b128 v[160:163], v236 offset:12288
	ds_read_b128 v[156:159], v236 offset:12800
	ds_read_b128 v[152:155], v236 offset:14336
	ds_read_b128 v[148:151], v236 offset:14848
	v_max3_f32 v3, v3, v22, v23
	v_max3_f32 v4, v4, v44, v45
	v_cmp_gt_u32_e64 s[6:7], 32, v224
	v_max3_f32 v3, v3, v42, v43
	v_max3_f32 v4, v4, v28, v29
	s_waitcnt vmcnt(2) lgkmcnt(0)
	s_barrier
	s_cmp_lt_i32 s19, 2
	v_max3_f32 v3, v3, v26, v27
	v_max3_f32 v4, v4, v48, v49
	s_nop 0
	v_writelane_b32 v252, s6, 41
	v_max3_f32 v3, v3, v46, v47
	v_max3_f32 v4, v4, v32, v33
	s_nop 0
	v_max3_f32 v3, v3, v30, v31
	s_nop 0
	v_max_f32_e32 v3, v3, v4
	v_writelane_b32 v252, s7, 42
	v_mov_b32_e32 v4, v3
	s_nop 1
	v_permlane32_swap_b32_e32 v3, v4
	v_max_f32_e32 v3, v3, v4
	v_writelane_b32 v252, s48, 43
	v_add_f32_e32 v231, v1, v3
	v_sub_f32_e32 v4, v34, v3
	v_sub_f32_e32 v5, v18, v3
	v_sub_f32_e32 v6, v35, v3
	v_sub_f32_e32 v7, v19, v3
	v_sub_f32_e32 v8, v36, v3
	v_sub_f32_e32 v9, v20, v3
	v_sub_f32_e32 v10, v37, v3
	v_sub_f32_e32 v11, v21, v3
	v_sub_f32_e32 v12, v38, v3
	v_sub_f32_e32 v13, v22, v3
	v_sub_f32_e32 v14, v39, v3
	v_sub_f32_e32 v15, v23, v3
	v_sub_f32_e32 v17, v40, v3
	v_sub_f32_e32 v18, v24, v3
	v_sub_f32_e32 v19, v41, v3
	v_sub_f32_e32 v20, v25, v3
	v_sub_f32_e32 v21, v42, v3
	v_sub_f32_e32 v22, v26, v3
	v_sub_f32_e32 v23, v43, v3
	v_sub_f32_e32 v24, v27, v3
	v_sub_f32_e32 v25, v44, v3
	v_sub_f32_e32 v26, v28, v3
	v_sub_f32_e32 v27, v45, v3
	v_sub_f32_e32 v28, v29, v3
	v_sub_f32_e32 v29, v46, v3
	v_sub_f32_e32 v30, v30, v3
	v_sub_f32_e32 v34, v47, v3
	v_sub_f32_e32 v31, v31, v3
	v_sub_f32_e32 v35, v48, v3
	v_sub_f32_e32 v32, v32, v3
	v_sub_f32_e32 v36, v49, v3
	v_sub_f32_e32 v3, v33, v3
	s_nop 0
	v_exp_f32_e32 v64, v4
	v_exp_f32_e32 v65, v6
	v_exp_f32_e32 v66, v8
	v_exp_f32_e32 v67, v10
	v_exp_f32_e32 v68, v12
	v_exp_f32_e32 v69, v14
	v_exp_f32_e32 v70, v17
	v_exp_f32_e32 v71, v19
	v_exp_f32_e32 v72, v21
	v_exp_f32_e32 v73, v23
	v_exp_f32_e32 v74, v25
	v_exp_f32_e32 v75, v27
	v_exp_f32_e32 v76, v29
	v_exp_f32_e32 v77, v34
	v_exp_f32_e32 v78, v35
	v_exp_f32_e32 v79, v36
	v_exp_f32_e32 v80, v5
	v_exp_f32_e32 v81, v7
	v_exp_f32_e32 v82, v9
	v_exp_f32_e32 v83, v11
	v_exp_f32_e32 v84, v13
	v_exp_f32_e32 v85, v15
	v_exp_f32_e32 v86, v18
	v_exp_f32_e32 v87, v20
	v_exp_f32_e32 v88, v22
	v_exp_f32_e32 v89, v24
	v_exp_f32_e32 v90, v26
	v_exp_f32_e32 v91, v28
	v_exp_f32_e32 v92, v30
	v_exp_f32_e32 v93, v31
	v_exp_f32_e32 v94, v32
	v_exp_f32_e32 v95, v3
	v_writelane_b32 v252, vcc_lo, 44
	s_cbranch_scc1 .LBB0_689
;     ...
;     float mhat = (MODE == 0) ? bref : 0.f, l_reg = 0.f; f32x16 o[2]; o[0] = f32x16{}; o[1] = f32x16{}; f32x16 negm = f32x16{};
;     if (MODE == 0) { _Pragma("unroll") for (int r = 0; r < 16; ++r) negm[r] = -bref; }
;     if (MODE != 1) asm volatile("" : "+v"(negm));
;     int na_gr = 0, na_rs = 0, na_qc = 0, na_cs = 0;
;     if (MODE == 1) { na_gr = r0 + (wid >> 1); na_rs = min(max(na_gr - 4, 0), 120); na_qc = 32 * (wid & 1) + r32; na_cs = min(max(na_qc - 8, 0), 48); }
	v_lshlrev_b32_e32 v0, 2, v230
	v_sub_u32_e32 v2, v0, v232
	v_cmp_gt_u32_e64 s[6:7], 16, v2
	v_or_b32_e32 v2, 32, v0
	v_sub_u32_e32 v2, v2, v232
	v_cmp_gt_u32_e64 s[8:9], 16, v2
	v_or_b32_e32 v2, 1, v0
	v_sub_u32_e32 v2, v2, v232
	v_cmp_gt_u32_e64 s[10:11], 16, v2
	v_or_b32_e32 v2, 33, v0
	v_sub_u32_e32 v2, v2, v232
	v_cmp_gt_u32_e64 s[12:13], 16, v2
	v_or_b32_e32 v2, 2, v0
	v_sub_u32_e32 v2, v2, v232
	v_cmp_gt_u32_e64 s[14:15], 16, v2
	v_or_b32_e32 v2, 34, v0
	v_sub_u32_e32 v2, v2, v232
	v_cmp_gt_u32_e64 s[16:17], 16, v2
	v_or_b32_e32 v2, 3, v0
	v_sub_u32_e32 v2, v2, v232
	v_cmp_gt_u32_e64 s[18:19], 16, v2
	v_or_b32_e32 v2, 35, v0
	v_sub_u32_e32 v2, v2, v232
	s_mov_b32 s74, s20
	s_mov_b32 s2, s21
	v_cmp_gt_u32_e64 s[20:21], 16, v2
	v_or_b32_e32 v2, 8, v0
	v_sub_u32_e32 v2, v2, v232
	v_cmp_gt_u32_e64 s[22:23], 16, v2
	v_or_b32_e32 v2, 40, v0
	v_sub_u32_e32 v2, v2, v232
	v_cmp_gt_u32_e64 s[24:25], 16, v2
	v_or_b32_e32 v2, 9, v0
	v_sub_u32_e32 v2, v2, v232
	v_cmp_gt_u32_e64 s[26:27], 16, v2
	v_or_b32_e32 v2, 41, v0
	v_sub_u32_e32 v2, v2, v232
	v_writelane_b32 v252, s28, 45
	v_cmp_gt_u32_e64 s[28:29], 16, v2
	v_or_b32_e32 v2, 10, v0
	v_sub_u32_e32 v2, v2, v232
	v_cmp_gt_u32_e64 s[30:31], 16, v2
	v_or_b32_e32 v2, 42, v0
	v_sub_u32_e32 v2, v2, v232
	v_cmp_gt_u32_e64 s[34:35], 16, v2
	v_or_b32_e32 v2, 11, v0
	v_sub_u32_e32 v2, v2, v232
	v_cmp_gt_u32_e64 s[36:37], 16, v2
	v_or_b32_e32 v2, 43, v0
	v_sub_u32_e32 v2, v2, v232
	v_cmp_gt_u32_e64 s[38:39], 16, v2
	v_or_b32_e32 v2, 16, v0
	v_sub_u32_e32 v2, v2, v232
	v_cmp_gt_u32_e64 s[40:41], 16, v2
	v_or_b32_e32 v2, 48, v0
	v_sub_u32_e32 v2, v2, v232
	v_cmp_gt_u32_e64 s[42:43], 16, v2
	v_or_b32_e32 v2, 17, v0
	v_sub_u32_e32 v2, v2, v232
	v_cmp_gt_u32_e64 s[44:45], 16, v2
	v_or_b32_e32 v2, 49, v0
	v_sub_u32_e32 v2, v2, v232
	v_cmp_gt_u32_e64 s[46:47], 16, v2
	v_or_b32_e32 v2, 18, v0
	v_sub_u32_e32 v2, v2, v232
	v_cmp_gt_u32_e64 s[48:49], 16, v2
	v_or_b32_e32 v2, 50, v0
	v_sub_u32_e32 v2, v2, v232
	v_cmp_gt_u32_e64 s[50:51], 16, v2
	v_or_b32_e32 v2, 19, v0
	v_sub_u32_e32 v2, v2, v232
	v_cmp_gt_u32_e64 s[52:53], 16, v2
	v_or_b32_e32 v2, 51, v0
	v_sub_u32_e32 v2, v2, v232
	v_cmp_gt_u32_e64 s[54:55], 16, v2
	v_or_b32_e32 v2, 24, v0
	v_sub_u32_e32 v2, v2, v232
	v_cmp_gt_u32_e64 s[56:57], 16, v2
	v_or_b32_e32 v2, 56, v0
	v_sub_u32_e32 v2, v2, v232
	v_cmp_gt_u32_e64 s[58:59], 16, v2
	v_or_b32_e32 v2, 25, v0
	v_sub_u32_e32 v2, v2, v232
	v_cmp_gt_u32_e64 s[60:61], 16, v2
	v_or_b32_e32 v2, 57, v0
	v_sub_u32_e32 v2, v2, v232
	v_cmp_gt_u32_e64 s[62:63], 16, v2
	v_or_b32_e32 v2, 26, v0
	v_sub_u32_e32 v2, v2, v232
	v_cmp_gt_u32_e64 s[64:65], 16, v2
	v_or_b32_e32 v2, 58, v0
	v_sub_u32_e32 v2, v2, v232
	v_cmp_gt_u32_e64 s[66:67], 16, v2
	v_or_b32_e32 v2, 27, v0
	v_or_b32_e32 v0, 59, v0
	s_mov_b32 s86, s2
	s_add_i32 s78, s2, -1
	s_min_u32 s2, s0, 4
	v_lshlrev_b32_e32 v197, 4, v230
	v_sub_u32_e32 v0, v0, v232
	s_add_i32 s72, vcc_lo, s2
	v_cmp_gt_u32_e64 s[70:71], 16, v0
	v_sub_u32_e32 v0, v197, v196
	s_mulk_i32 s72, 0x7c
	v_subrev_u32_e32 v0, s72, v0
	s_lshl_b32 s72, s5, 1
	s_and_b32 s72, s72, 0x80
	v_subrev_u32_e32 v0, s72, v0
	v_readlane_b32 s72, v254, 45
	v_sub_u32_e32 v2, v2, v232
	v_mov_b32_e32 v14, v1
	v_add_u32_e32 v198, s72, v0
	s_lshl_b32 s72, s2, 6
	v_mov_b32_e32 v15, v1
	v_cmp_gt_u32_e64 s[68:69], 16, v2
	s_sub_i32 s79, s1, s72
	s_sub_i32 s72, s0, s74
	v_mov_b32_e32 v0, v1
	v_mov_b32_e32 v2, v1
	v_mov_b32_e32 v3, v1
	v_mov_b32_e32 v4, v1
	v_mov_b32_e32 v5, v1
	v_mov_b32_e32 v6, v1
	v_mov_b32_e32 v7, v1
	v_mov_b32_e32 v8, v1
	v_mov_b32_e32 v9, v1
	v_mov_b32_e32 v10, v1
	v_mov_b32_e32 v11, v1
	v_mov_b32_e32 v12, v1
	v_mov_b32_e32 v13, v1
	v_mov_b64_e32 v[62:63], v[14:15]
	v_mov_b64_e32 v[46:47], v[14:15]
	s_mov_b32 s73, 1
	s_mov_b32 s83, -1
	s_mov_b32 s87, s74
	s_sub_i32 s80, s72, s2
	s_mov_b32 s81, 0
	s_movk_i32 s72, 0x4000
	v_mov_b32_e32 v239, 0
	v_mov_b64_e32 v[60:61], v[12:13]
	v_mov_b64_e32 v[58:59], v[10:11]
	v_mov_b64_e32 v[56:57], v[8:9]
	v_mov_b64_e32 v[54:55], v[6:7]
	v_mov_b64_e32 v[52:53], v[4:5]
	v_mov_b64_e32 v[50:51], v[2:3]
	v_mov_b64_e32 v[48:49], v[0:1]
	v_mov_b64_e32 v[44:45], v[12:13]
	v_mov_b64_e32 v[42:43], v[10:11]
	v_mov_b64_e32 v[40:41], v[8:9]
	v_mov_b64_e32 v[38:39], v[6:7]
	v_mov_b64_e32 v[36:37], v[4:5]
	v_mov_b64_e32 v[34:35], v[2:3]
	v_mov_b64_e32 v[32:33], v[0:1]
	s_mov_b32 s74, 0
